# v15 with the SwiGLU hidden-activation stores as plain (not nontemporal) stores
# speedup vs baseline: 1.0380x; 1.0380x over previous
; __device__ __forceinline__ unsigned cvt_pk_bf16(float lo, float hi) { unsigned r; asm volatile("v_cvt_pk_bf16_f32 %0, %1, %2" : "=v"(r) : "v"(lo), "v"(hi)); return r; }
; #define SWG_(gv, uv) ((gv) * (uv) * __builtin_amdgcn_rcpf(1.0f + __builtin_amdgcn_exp2f(-(gv))))
;     __device__ __forceinline__ unsigned u(int i) const { return (unsigned)__builtin_amdgcn_readfirstlane((int)d[i]); }
; __device__ __forceinline__ float row_scale(const float* ssqA, const float* ssqB, int row) {
;     float r = __builtin_amdgcn_rsqf(ssqA[row] * (1.0f / 1024.0f) + 1e-6f);
;     if (ssqB) r *= __builtin_amdgcn_rsqf(r * r * ssqB[row] * (1.0f / 1024.0f) + 1e-6f);
;     return r;
; }
;     static __device__ __forceinline__ void run(const f32x4 (&acc)[2][2][4][2], const Unit& u, int wr, int wc, int fr, int fq, bf16_t* H, int ldh, const float* ssqA, const float* ssqB, const float* bvec) {
;         const int b = (u.pm * BM) >> 13; const int row0 = u.pm * BM + wr * 64 + fr; const int col0 = u.pn * 128 + wc * 32 + 8 * fq;
;         const float* bp = bvec + ((unsigned)b * (unsigned)(2 * ldh) + (unsigned)(u.pn * BM + wc * 32 + 8 * fq));
;         const f32x4 bg0 = *(const f32x4*)bp * 1.4426950408889634f, bg1 = *(const f32x4*)(bp + 4) * 1.4426950408889634f, bu0 = *(const f32x4*)(bp + HALF) * 0.6931471805599453f, bu1 = *(const f32x4*)(bp + HALF + 4) * 0.6931471805599453f;
;     ...
; #pragma unroll
;         for (int ai = 0; ai < 2; ++ai)
; #pragma unroll
;             for (int m = 0; m < 4; ++m) {
;                 const int row = row0 + ai * HALF + m * 16; const float r = row_scale(ssqA, ssqB, row); const float rg = r * 1.4426950408889634f, ru = r * 0.6931471805599453f;
;                 bf16_t* p = H + ((unsigned)row * (unsigned)ldh + (unsigned)col0);
;                 const f32x4 g0 = acc[ai][0][m][0] * rg + bg0, g1 = acc[ai][0][m][1] * rg + bg1, u0 = acc[ai][1][m][0] * ru + bu0, u1 = acc[ai][1][m][1] * ru + bu1;
;                 u32x4 w;
;                 w.x = cvt_pk_bf16(SWG_(g0[0], u0[0]), SWG_(g0[1], u0[1]));
;                 w.y = cvt_pk_bf16(SWG_(g0[2], u0[2]), SWG_(g0[3], u0[3]));
;                 w.z = cvt_pk_bf16(SWG_(g1[0], u1[0]), SWG_(g1[1], u1[1]));
;                 w.w = cvt_pk_bf16(SWG_(g1[2], u1[2]), SWG_(g1[3], u1[3]));
;                 __builtin_nontemporal_store(w, (u32x4*)p);
.LBB0_549:
	s_lshl_b32 s9, s62, 7
	s_or_b32 s8, s8, s9
	v_or_b32_e32 v149, s8, v150
	s_mov_b32 s8, 0x3fb8aa3b
	v_pk_mul_f32 v[142:143], v[142:143], s[8:9] op_sel_hi:[1,0]
	v_pk_mul_f32 v[140:141], v[140:141], s[8:9] op_sel_hi:[1,0]
	v_pk_mul_f32 v[138:139], v[138:139], s[8:9] op_sel_hi:[1,0]
	v_pk_mul_f32 v[136:137], v[136:137], s[8:9] op_sel_hi:[1,0]
	s_mov_b32 s8, 0x3f317218
	v_mul_f32_e32 v150, 0x3fb8aa3b, v151
	v_pk_mul_f32 v[134:135], v[134:135], s[8:9] op_sel_hi:[1,0]
	v_pk_mul_f32 v[132:133], v[132:133], s[8:9] op_sel_hi:[1,0]
	v_mul_f32_e32 v152, 0x3f317218, v151
	v_pk_fma_f32 v[124:125], v[124:125], v[150:151], v[140:141] op_sel_hi:[1,0,1]
	v_pk_fma_f32 v[118:119], v[118:119], v[152:153], v[134:135] op_sel_hi:[1,0,1]
	v_pk_fma_f32 v[116:117], v[116:117], v[152:153], v[132:133] op_sel_hi:[1,0,1]
	v_exp_f32_e64 v153, -v124
	v_pk_mul_f32 v[130:131], v[130:131], s[8:9] op_sel_hi:[1,0]
	v_pk_mul_f32 v[128:129], v[128:129], s[8:9] op_sel_hi:[1,0]
	v_pk_fma_f32 v[126:127], v[126:127], v[150:151], v[142:143] op_sel_hi:[1,0,1]
	v_pk_fma_f32 v[122:123], v[122:123], v[150:151], v[138:139] op_sel_hi:[1,0,1]
	v_pk_fma_f32 v[120:121], v[120:121], v[150:151], v[136:137] op_sel_hi:[1,0,1]
	v_pk_fma_f32 v[150:151], v[114:115], v[152:153], v[130:131] op_sel_hi:[1,0,1]
	v_pk_fma_f32 v[114:115], v[112:113], v[152:153], v[128:129] op_sel_hi:[1,0,1]
	v_exp_f32_e64 v112, -v125
	v_add_f32_e32 v113, 1.0, v153
	v_rcp_f32_e32 v113, v113
	v_mul_f32_e32 v116, v124, v116
	v_add_f32_e32 v112, 1.0, v112
	v_rcp_f32_e32 v112, v112
	v_mul_f32_e32 v113, v116, v113
	v_mul_f32_e32 v116, v125, v117
	v_exp_f32_e64 v117, -v126
	v_mul_f32_e32 v112, v116, v112
	v_cvt_pk_bf16_f32 v112, v113, v112
	v_exp_f32_e64 v113, -v127
	v_add_f32_e32 v116, 1.0, v117
	v_rcp_f32_e32 v116, v116
	v_mul_f32_e32 v117, v126, v118
	v_add_f32_e32 v113, 1.0, v113
	v_rcp_f32_e32 v113, v113
	v_mul_f32_e32 v116, v117, v116
	v_mul_f32_e32 v117, v127, v119
	v_exp_f32_e64 v118, -v120
	v_mul_f32_e32 v113, v117, v113
	v_cvt_pk_bf16_f32 v113, v116, v113
	v_exp_f32_e64 v116, -v121
	v_add_f32_e32 v117, 1.0, v118
	v_rcp_f32_e32 v117, v117
	v_mul_f32_e32 v114, v120, v114
	v_add_f32_e32 v116, 1.0, v116
	v_rcp_f32_e32 v116, v116
	v_mul_f32_e32 v114, v114, v117
	v_mul_f32_e32 v115, v121, v115
	v_exp_f32_e64 v117, -v122
	v_mul_f32_e32 v115, v115, v116
	v_exp_f32_e64 v116, -v123
	v_cvt_pk_bf16_f32 v114, v114, v115
	v_add_f32_e32 v115, 1.0, v117
	v_rcp_f32_e32 v115, v115
	v_add_f32_e32 v116, 1.0, v116
	v_rcp_f32_e32 v116, v116
	v_mul_lo_u32 v148, s26, v148
	v_add_u32_e32 v176, v148, v149
	v_mul_f32_e32 v117, v122, v150
	v_lshl_add_u64 v[154:155], v[176:177], 1, s[2:3]
	v_mul_f32_e32 v115, v117, v115
	v_mul_f32_e32 v117, v123, v151
	v_mul_f32_e32 v116, v117, v116
	v_cvt_pk_bf16_f32 v115, v115, v116
	global_store_dwordx4 v[154:155], v[112:115], off
	s_nop 0
	s_andn2_b64 vcc, exec, s[10:11]
	v_cndmask_b32_e64 v113, 0, 1, s[10:11]
	v_cmp_ne_u32_e64 s[8:9], 1, v113
	s_waitcnt vmcnt(7)
	v_fmamk_f32 v112, v180, 0x3a800000, v222
	v_rsq_f32_e32 v112, v112
	s_cbranch_vccnz .LBB0_551
	global_load_dword v113, v[146:147], off offset:64
	v_mul_f32_e32 v114, v112, v112
	s_waitcnt vmcnt(0)
	v_mul_f32_e32 v113, v114, v113
	v_fmamk_f32 v113, v113, 0x3a800000, v222
	v_rsq_f32_e32 v113, v113
	s_nop 0
	v_mul_f32_e32 v112, v112, v113
.LBB0_551:
	v_mul_f32_e32 v114, 0x3fb8aa3b, v112
	v_pk_fma_f32 v[108:109], v[108:109], v[114:115], v[140:141] op_sel_hi:[1,0,1]
	v_mul_f32_e32 v116, 0x3f317218, v112
	v_exp_f32_e64 v113, -v108
	v_pk_fma_f32 v[110:111], v[110:111], v[114:115], v[142:143] op_sel_hi:[1,0,1]
	v_pk_fma_f32 v[106:107], v[106:107], v[114:115], v[138:139] op_sel_hi:[1,0,1]
	v_pk_fma_f32 v[104:105], v[104:105], v[114:115], v[136:137] op_sel_hi:[1,0,1]
	v_pk_fma_f32 v[114:115], v[98:99], v[116:117], v[130:131] op_sel_hi:[1,0,1]
	v_pk_fma_f32 v[98:99], v[96:97], v[116:117], v[128:129] op_sel_hi:[1,0,1]
	v_exp_f32_e64 v96, -v109
	v_add_f32_e32 v97, 1.0, v113
	v_rcp_f32_e32 v97, v97
	v_pk_fma_f32 v[100:101], v[100:101], v[116:117], v[132:133] op_sel_hi:[1,0,1]
	v_add_f32_e32 v96, 1.0, v96
	v_rcp_f32_e32 v96, v96
	v_mul_f32_e32 v100, v108, v100
	v_mul_f32_e32 v97, v100, v97
	v_mul_f32_e32 v100, v109, v101
	v_exp_f32_e64 v101, -v110
	v_mul_f32_e32 v96, v100, v96
	v_cvt_pk_bf16_f32 v96, v97, v96
	v_exp_f32_e64 v97, -v111
	v_add_f32_e32 v100, 1.0, v101
	v_rcp_f32_e32 v100, v100
	v_pk_fma_f32 v[102:103], v[102:103], v[116:117], v[134:135] op_sel_hi:[1,0,1]
	v_add_f32_e32 v97, 1.0, v97
	v_rcp_f32_e32 v97, v97
	v_mul_f32_e32 v101, v110, v102
	v_mul_f32_e32 v100, v101, v100
	v_mul_f32_e32 v101, v111, v103
	v_exp_f32_e64 v102, -v104
	v_mul_f32_e32 v97, v101, v97
	v_cvt_pk_bf16_f32 v97, v100, v97
	v_exp_f32_e64 v100, -v105
	v_add_f32_e32 v101, 1.0, v102
	v_rcp_f32_e32 v101, v101
	v_mul_f32_e32 v98, v104, v98
	v_add_f32_e32 v100, 1.0, v100
	v_rcp_f32_e32 v100, v100
	v_mul_f32_e32 v98, v98, v101
	v_mul_f32_e32 v99, v105, v99
	v_exp_f32_e64 v101, -v106
	v_mul_f32_e32 v99, v99, v100
	v_exp_f32_e64 v100, -v107
	v_cvt_pk_bf16_f32 v98, v98, v99
	v_add_f32_e32 v99, 1.0, v101
	v_rcp_f32_e32 v99, v99
	v_add_f32_e32 v100, 1.0, v100
	s_lshl_b32 s10, s26, 4
	v_rcp_f32_e32 v100, v100
	v_add_u32_e32 v112, s10, v148
	v_add_u32_e32 v176, v112, v149
	v_mul_f32_e32 v101, v106, v114
	v_lshl_add_u64 v[118:119], v[176:177], 1, s[2:3]
	v_mul_f32_e32 v99, v101, v99
	v_mul_f32_e32 v101, v107, v115
	v_mul_f32_e32 v100, v101, v100
	v_cvt_pk_bf16_f32 v99, v99, v100
	global_store_dwordx4 v[118:119], v[96:99], off
	s_nop 0
	s_and_b64 vcc, exec, s[8:9]
	s_waitcnt vmcnt(7)
	v_fmamk_f32 v96, v181, 0x3a800000, v222
	v_rsq_f32_e32 v96, v96
	s_cbranch_vccnz .LBB0_553
	global_load_dword v97, v[146:147], off offset:128
	v_mul_f32_e32 v98, v96, v96
	s_waitcnt vmcnt(0)
	v_mul_f32_e32 v97, v98, v97
	v_fmamk_f32 v97, v97, 0x3a800000, v222
	v_rsq_f32_e32 v97, v97
	s_nop 0
	v_mul_f32_e32 v96, v96, v97
; __device__ __forceinline__ unsigned cvt_pk_bf16(float lo, float hi) { unsigned r; asm volatile("v_cvt_pk_bf16_f32 %0, %1, %2" : "=v"(r) : "v"(lo), "v"(hi)); return r; }
; #define SWG_(gv, uv) ((gv) * (uv) * __builtin_amdgcn_rcpf(1.0f + __builtin_amdgcn_exp2f(-(gv))))
;     template <class T> __device__ __forceinline__ T* p(int i) const { const unsigned long long lo = u(i), hi = u(i + 1); return (T*)(__attribute__((address_space(1))) T*)((hi << 32) | lo); }
; __device__ __forceinline__ float row_scale(const float* ssqA, const float* ssqB, int row) {
;     float r = __builtin_amdgcn_rsqf(ssqA[row] * (1.0f / 1024.0f) + 1e-6f);
;     if (ssqB) r *= __builtin_amdgcn_rsqf(r * r * ssqB[row] * (1.0f / 1024.0f) + 1e-6f);
;     static __device__ __forceinline__ void run(const f32x4 (&acc)[2][2][4][2], const Unit& u, int wr, int wc, int fr, int fq, bf16_t* H, int ldh, const float* ssqA, const float* ssqB, const float* bvec) {
;     ...
;                 const int row = row0 + ai * HALF + m * 16; const float r = row_scale(ssqA, ssqB, row); const float rg = r * 1.4426950408889634f, ru = r * 0.6931471805599453f;
;                 bf16_t* p = H + ((unsigned)row * (unsigned)ldh + (unsigned)col0);
;                 const f32x4 g0 = acc[ai][0][m][0] * rg + bg0, g1 = acc[ai][0][m][1] * rg + bg1, u0 = acc[ai][1][m][0] * ru + bu0, u1 = acc[ai][1][m][1] * ru + bu1;
;                 u32x4 w;
;                 w.x = cvt_pk_bf16(SWG_(g0[0], u0[0]), SWG_(g0[1], u0[1]));
;                 w.y = cvt_pk_bf16(SWG_(g0[2], u0[2]), SWG_(g0[3], u0[3]));
;                 w.z = cvt_pk_bf16(SWG_(g1[0], u1[0]), SWG_(g1[1], u1[1]));
;                 w.w = cvt_pk_bf16(SWG_(g1[2], u1[2]), SWG_(g1[3], u1[3]));
;                 __builtin_nontemporal_store(w, (u32x4*)p);
.LBB0_553:
	v_mul_f32_e32 v98, 0x3fb8aa3b, v96
	v_pk_fma_f32 v[92:93], v[92:93], v[98:99], v[140:141] op_sel_hi:[1,0,1]
	v_mul_f32_e32 v100, 0x3f317218, v96
	v_exp_f32_e64 v97, -v92
	v_pk_fma_f32 v[94:95], v[94:95], v[98:99], v[142:143] op_sel_hi:[1,0,1]
	v_pk_fma_f32 v[90:91], v[90:91], v[98:99], v[138:139] op_sel_hi:[1,0,1]
	v_pk_fma_f32 v[88:89], v[88:89], v[98:99], v[136:137] op_sel_hi:[1,0,1]
	v_pk_fma_f32 v[98:99], v[82:83], v[100:101], v[130:131] op_sel_hi:[1,0,1]
	v_pk_fma_f32 v[82:83], v[80:81], v[100:101], v[128:129] op_sel_hi:[1,0,1]
	v_exp_f32_e64 v80, -v93
	v_add_f32_e32 v81, 1.0, v97
	v_rcp_f32_e32 v81, v81
	v_pk_fma_f32 v[84:85], v[84:85], v[100:101], v[132:133] op_sel_hi:[1,0,1]
	v_add_f32_e32 v80, 1.0, v80
	v_rcp_f32_e32 v80, v80
	v_mul_f32_e32 v84, v92, v84
	v_mul_f32_e32 v81, v84, v81
	v_mul_f32_e32 v84, v93, v85
	v_exp_f32_e64 v85, -v94
	v_mul_f32_e32 v80, v84, v80
	v_cvt_pk_bf16_f32 v80, v81, v80
	v_exp_f32_e64 v81, -v95
	v_add_f32_e32 v84, 1.0, v85
	v_rcp_f32_e32 v84, v84
	v_pk_fma_f32 v[86:87], v[86:87], v[100:101], v[134:135] op_sel_hi:[1,0,1]
	v_add_f32_e32 v81, 1.0, v81
	v_rcp_f32_e32 v81, v81
	v_mul_f32_e32 v85, v94, v86
	v_mul_f32_e32 v84, v85, v84
	v_mul_f32_e32 v85, v95, v87
	v_exp_f32_e64 v86, -v88
	v_mul_f32_e32 v81, v85, v81
	v_cvt_pk_bf16_f32 v81, v84, v81
	v_exp_f32_e64 v84, -v89
	v_add_f32_e32 v85, 1.0, v86
	v_rcp_f32_e32 v85, v85
	v_mul_f32_e32 v82, v88, v82
	v_add_f32_e32 v84, 1.0, v84
	v_rcp_f32_e32 v84, v84
	v_mul_f32_e32 v82, v82, v85
	v_mul_f32_e32 v83, v89, v83
	v_exp_f32_e64 v85, -v90
	v_mul_f32_e32 v83, v83, v84
	v_exp_f32_e64 v84, -v91
	v_cvt_pk_bf16_f32 v82, v82, v83
	v_add_f32_e32 v83, 1.0, v85
	v_rcp_f32_e32 v83, v83
	v_add_f32_e32 v84, 1.0, v84
	v_rcp_f32_e32 v84, v84
	v_add_u32_e32 v96, s10, v112
	v_add_u32_e32 v176, v96, v149
	v_mul_f32_e32 v85, v90, v98
	v_lshl_add_u64 v[102:103], v[176:177], 1, s[2:3]
	v_mul_f32_e32 v83, v85, v83
	v_mul_f32_e32 v85, v91, v99
	v_mul_f32_e32 v84, v85, v84
	v_cvt_pk_bf16_f32 v83, v83, v84
	global_store_dwordx4 v[102:103], v[80:83], off
	s_nop 0
	s_and_b64 vcc, exec, s[8:9]
	s_waitcnt vmcnt(7)
	v_fmamk_f32 v80, v182, 0x3a800000, v222
	v_rsq_f32_e32 v80, v80
	s_cbranch_vccnz .LBB0_555
	global_load_dword v81, v[146:147], off offset:192
	v_mul_f32_e32 v82, v80, v80
	s_waitcnt vmcnt(0)
	v_mul_f32_e32 v81, v82, v81
	v_fmamk_f32 v81, v81, 0x3a800000, v222
	v_rsq_f32_e32 v81, v81
	s_nop 0
	v_mul_f32_e32 v80, v80, v81
.LBB0_555:
	v_mul_f32_e32 v82, 0x3fb8aa3b, v80
	v_pk_fma_f32 v[76:77], v[76:77], v[82:83], v[140:141] op_sel_hi:[1,0,1]
	v_mul_f32_e32 v84, 0x3f317218, v80
	v_exp_f32_e64 v81, -v76
	v_pk_fma_f32 v[78:79], v[78:79], v[82:83], v[142:143] op_sel_hi:[1,0,1]
	v_pk_fma_f32 v[74:75], v[74:75], v[82:83], v[138:139] op_sel_hi:[1,0,1]
	v_pk_fma_f32 v[72:73], v[72:73], v[82:83], v[136:137] op_sel_hi:[1,0,1]
	v_pk_fma_f32 v[82:83], v[66:67], v[84:85], v[130:131] op_sel_hi:[1,0,1]
	v_pk_fma_f32 v[66:67], v[64:65], v[84:85], v[128:129] op_sel_hi:[1,0,1]
	v_exp_f32_e64 v64, -v77
	v_add_f32_e32 v65, 1.0, v81
	v_rcp_f32_e32 v65, v65
	v_pk_fma_f32 v[68:69], v[68:69], v[84:85], v[132:133] op_sel_hi:[1,0,1]
	v_add_f32_e32 v64, 1.0, v64
	v_rcp_f32_e32 v64, v64
	v_mul_f32_e32 v68, v76, v68
	v_mul_f32_e32 v65, v68, v65
	v_mul_f32_e32 v68, v77, v69
	v_exp_f32_e64 v69, -v78
	v_mul_f32_e32 v64, v68, v64
	v_cvt_pk_bf16_f32 v64, v65, v64
	v_exp_f32_e64 v65, -v79
	v_add_f32_e32 v68, 1.0, v69
	v_rcp_f32_e32 v68, v68
	v_pk_fma_f32 v[70:71], v[70:71], v[84:85], v[134:135] op_sel_hi:[1,0,1]
	v_add_f32_e32 v65, 1.0, v65
	v_rcp_f32_e32 v65, v65
	v_mul_f32_e32 v69, v78, v70
	v_mul_f32_e32 v68, v69, v68
	v_mul_f32_e32 v69, v79, v71
	v_exp_f32_e64 v70, -v72
	v_mul_f32_e32 v65, v69, v65
	v_cvt_pk_bf16_f32 v65, v68, v65
	v_exp_f32_e64 v68, -v73
	v_add_f32_e32 v69, 1.0, v70
	v_rcp_f32_e32 v69, v69
	v_mul_f32_e32 v66, v72, v66
	v_add_f32_e32 v68, 1.0, v68
	v_rcp_f32_e32 v68, v68
	v_mul_f32_e32 v66, v66, v69
	v_mul_f32_e32 v67, v73, v67
	v_exp_f32_e64 v69, -v74
	v_mul_f32_e32 v67, v67, v68
	v_exp_f32_e64 v68, -v75
	v_cvt_pk_bf16_f32 v66, v66, v67
	v_add_f32_e32 v67, 1.0, v69
	v_rcp_f32_e32 v67, v67
	v_add_f32_e32 v68, 1.0, v68
	v_rcp_f32_e32 v68, v68
	v_add_u32_e32 v80, s10, v96
	v_add_u32_e32 v176, v80, v149
	v_mul_f32_e32 v69, v74, v82
	v_lshl_add_u64 v[86:87], v[176:177], 1, s[2:3]
	v_mul_f32_e32 v67, v69, v67
	v_mul_f32_e32 v69, v75, v83
	v_mul_f32_e32 v68, v69, v68
	v_cvt_pk_bf16_f32 v67, v67, v68
	global_store_dwordx4 v[86:87], v[64:67], off
	s_nop 0
	s_and_b64 vcc, exec, s[8:9]
	s_waitcnt vmcnt(7)
	v_fmamk_f32 v64, v183, 0x3a800000, v222
	v_rsq_f32_e32 v64, v64
	s_cbranch_vccnz .LBB0_557
	global_load_dword v65, v[146:147], off offset:512
	v_mul_f32_e32 v66, v64, v64
	s_waitcnt vmcnt(0)
	v_mul_f32_e32 v65, v66, v65
	v_fmamk_f32 v65, v65, 0x3a800000, v222
	v_rsq_f32_e32 v65, v65
	s_nop 0
	v_mul_f32_e32 v64, v64, v65
; __device__ __forceinline__ unsigned cvt_pk_bf16(float lo, float hi) { unsigned r; asm volatile("v_cvt_pk_bf16_f32 %0, %1, %2" : "=v"(r) : "v"(lo), "v"(hi)); return r; }
; #define SWG_(gv, uv) ((gv) * (uv) * __builtin_amdgcn_rcpf(1.0f + __builtin_amdgcn_exp2f(-(gv))))
;     template <class T> __device__ __forceinline__ T* p(int i) const { const unsigned long long lo = u(i), hi = u(i + 1); return (T*)(__attribute__((address_space(1))) T*)((hi << 32) | lo); }
; __device__ __forceinline__ float row_scale(const float* ssqA, const float* ssqB, int row) {
;     float r = __builtin_amdgcn_rsqf(ssqA[row] * (1.0f / 1024.0f) + 1e-6f);
;     if (ssqB) r *= __builtin_amdgcn_rsqf(r * r * ssqB[row] * (1.0f / 1024.0f) + 1e-6f);
;     static __device__ __forceinline__ void run(const f32x4 (&acc)[2][2][4][2], const Unit& u, int wr, int wc, int fr, int fq, bf16_t* H, int ldh, const float* ssqA, const float* ssqB, const float* bvec) {
;     ...
;                 const int row = row0 + ai * HALF + m * 16; const float r = row_scale(ssqA, ssqB, row); const float rg = r * 1.4426950408889634f, ru = r * 0.6931471805599453f;
;                 bf16_t* p = H + ((unsigned)row * (unsigned)ldh + (unsigned)col0);
;                 const f32x4 g0 = acc[ai][0][m][0] * rg + bg0, g1 = acc[ai][0][m][1] * rg + bg1, u0 = acc[ai][1][m][0] * ru + bu0, u1 = acc[ai][1][m][1] * ru + bu1;
;                 u32x4 w;
;                 w.x = cvt_pk_bf16(SWG_(g0[0], u0[0]), SWG_(g0[1], u0[1]));
;                 w.y = cvt_pk_bf16(SWG_(g0[2], u0[2]), SWG_(g0[3], u0[3]));
;                 w.z = cvt_pk_bf16(SWG_(g1[0], u1[0]), SWG_(g1[1], u1[1]));
;                 w.w = cvt_pk_bf16(SWG_(g1[2], u1[2]), SWG_(g1[3], u1[3]));
;                 __builtin_nontemporal_store(w, (u32x4*)p);
.LBB0_557:
	v_mul_f32_e32 v66, 0x3fb8aa3b, v64
	v_pk_fma_f32 v[60:61], v[60:61], v[66:67], v[140:141] op_sel_hi:[1,0,1]
	v_mul_f32_e32 v68, 0x3f317218, v64
	v_exp_f32_e64 v65, -v60
	v_pk_fma_f32 v[62:63], v[62:63], v[66:67], v[142:143] op_sel_hi:[1,0,1]
	v_pk_fma_f32 v[58:59], v[58:59], v[66:67], v[138:139] op_sel_hi:[1,0,1]
	v_pk_fma_f32 v[56:57], v[56:57], v[66:67], v[136:137] op_sel_hi:[1,0,1]
	v_pk_fma_f32 v[66:67], v[50:51], v[68:69], v[130:131] op_sel_hi:[1,0,1]
	v_pk_fma_f32 v[50:51], v[48:49], v[68:69], v[128:129] op_sel_hi:[1,0,1]
	v_exp_f32_e64 v48, -v61
	v_add_f32_e32 v49, 1.0, v65
	v_rcp_f32_e32 v49, v49
	v_pk_fma_f32 v[52:53], v[52:53], v[68:69], v[132:133] op_sel_hi:[1,0,1]
	v_add_f32_e32 v48, 1.0, v48
	v_rcp_f32_e32 v48, v48
	v_mul_f32_e32 v52, v60, v52
	v_mul_f32_e32 v49, v52, v49
	v_mul_f32_e32 v52, v61, v53
	v_exp_f32_e64 v53, -v62
	v_mul_f32_e32 v48, v52, v48
	v_cvt_pk_bf16_f32 v48, v49, v48
	v_exp_f32_e64 v49, -v63
	v_add_f32_e32 v52, 1.0, v53
	v_rcp_f32_e32 v52, v52
	v_pk_fma_f32 v[54:55], v[54:55], v[68:69], v[134:135] op_sel_hi:[1,0,1]
	v_add_f32_e32 v49, 1.0, v49
	v_rcp_f32_e32 v49, v49
	v_mul_f32_e32 v53, v62, v54
	v_mul_f32_e32 v52, v53, v52
	v_mul_f32_e32 v53, v63, v55
	v_exp_f32_e64 v54, -v56
	v_mul_f32_e32 v49, v53, v49
	v_cvt_pk_bf16_f32 v49, v52, v49
	v_exp_f32_e64 v52, -v57
	v_add_f32_e32 v53, 1.0, v54
	v_rcp_f32_e32 v53, v53
	v_mul_f32_e32 v50, v56, v50
	v_add_f32_e32 v52, 1.0, v52
	v_rcp_f32_e32 v52, v52
	v_mul_f32_e32 v50, v50, v53
	v_mul_f32_e32 v51, v57, v51
	v_exp_f32_e64 v53, -v58
	v_mul_f32_e32 v51, v51, v52
	v_exp_f32_e64 v52, -v59
	v_cvt_pk_bf16_f32 v50, v50, v51
	v_add_f32_e32 v51, 1.0, v53
	v_rcp_f32_e32 v51, v51
	v_add_f32_e32 v52, 1.0, v52
	s_mulk_i32 s26, 0x50
	v_rcp_f32_e32 v52, v52
	v_add_u32_e32 v64, s26, v80
	v_add_u32_e32 v176, v64, v149
	v_mul_f32_e32 v53, v58, v66
	v_lshl_add_u64 v[70:71], v[176:177], 1, s[2:3]
	v_mul_f32_e32 v51, v53, v51
	v_mul_f32_e32 v53, v59, v67
	v_mul_f32_e32 v52, v53, v52
	v_cvt_pk_bf16_f32 v51, v51, v52
	global_store_dwordx4 v[70:71], v[48:51], off
	s_nop 0
	s_and_b64 vcc, exec, s[8:9]
	s_waitcnt vmcnt(7)
	v_fmamk_f32 v48, v184, 0x3a800000, v222
	v_rsq_f32_e32 v48, v48
	s_cbranch_vccnz .LBB0_559
	global_load_dword v49, v[146:147], off offset:576
	v_mul_f32_e32 v50, v48, v48
	s_waitcnt vmcnt(0)
	v_mul_f32_e32 v49, v50, v49
	v_fmamk_f32 v49, v49, 0x3a800000, v222
	v_rsq_f32_e32 v49, v49
	s_nop 0
	v_mul_f32_e32 v48, v48, v49
.LBB0_559:
	v_mul_f32_e32 v50, 0x3fb8aa3b, v48
	v_pk_fma_f32 v[44:45], v[44:45], v[50:51], v[140:141] op_sel_hi:[1,0,1]
	v_mul_f32_e32 v52, 0x3f317218, v48
	v_exp_f32_e64 v49, -v44
	v_pk_fma_f32 v[46:47], v[46:47], v[50:51], v[142:143] op_sel_hi:[1,0,1]
	v_pk_fma_f32 v[42:43], v[42:43], v[50:51], v[138:139] op_sel_hi:[1,0,1]
	v_pk_fma_f32 v[40:41], v[40:41], v[50:51], v[136:137] op_sel_hi:[1,0,1]
	v_pk_fma_f32 v[50:51], v[34:35], v[52:53], v[130:131] op_sel_hi:[1,0,1]
	v_pk_fma_f32 v[34:35], v[32:33], v[52:53], v[128:129] op_sel_hi:[1,0,1]
	v_exp_f32_e64 v32, -v45
	v_add_f32_e32 v33, 1.0, v49
	v_rcp_f32_e32 v33, v33
	v_pk_fma_f32 v[36:37], v[36:37], v[52:53], v[132:133] op_sel_hi:[1,0,1]
	v_add_f32_e32 v32, 1.0, v32
	v_rcp_f32_e32 v32, v32
	v_mul_f32_e32 v36, v44, v36
	v_mul_f32_e32 v33, v36, v33
	v_mul_f32_e32 v36, v45, v37
	v_exp_f32_e64 v37, -v46
	v_mul_f32_e32 v32, v36, v32
	v_cvt_pk_bf16_f32 v32, v33, v32
	v_exp_f32_e64 v33, -v47
	v_add_f32_e32 v36, 1.0, v37
	v_rcp_f32_e32 v36, v36
	v_pk_fma_f32 v[38:39], v[38:39], v[52:53], v[134:135] op_sel_hi:[1,0,1]
	v_add_f32_e32 v33, 1.0, v33
	v_rcp_f32_e32 v33, v33
	v_mul_f32_e32 v37, v46, v38
	v_mul_f32_e32 v36, v37, v36
	v_mul_f32_e32 v37, v47, v39
	v_exp_f32_e64 v38, -v40
	v_mul_f32_e32 v33, v37, v33
	v_cvt_pk_bf16_f32 v33, v36, v33
	v_exp_f32_e64 v36, -v41
	v_add_f32_e32 v37, 1.0, v38
	v_rcp_f32_e32 v37, v37
	v_mul_f32_e32 v34, v40, v34
	v_add_f32_e32 v36, 1.0, v36
	v_rcp_f32_e32 v36, v36
	v_mul_f32_e32 v34, v34, v37
	v_mul_f32_e32 v35, v41, v35
	v_exp_f32_e64 v37, -v42
	v_mul_f32_e32 v35, v35, v36
	v_exp_f32_e64 v36, -v43
	v_cvt_pk_bf16_f32 v34, v34, v35
	v_add_f32_e32 v35, 1.0, v37
	v_rcp_f32_e32 v35, v35
	v_add_f32_e32 v36, 1.0, v36
	v_rcp_f32_e32 v36, v36
	v_add_u32_e32 v48, s10, v64
	v_add_u32_e32 v176, v48, v149
	v_mul_f32_e32 v37, v42, v50
	v_lshl_add_u64 v[54:55], v[176:177], 1, s[2:3]
	v_mul_f32_e32 v35, v37, v35
	v_mul_f32_e32 v37, v43, v51
	v_mul_f32_e32 v36, v37, v36
	v_cvt_pk_bf16_f32 v35, v35, v36
	global_store_dwordx4 v[54:55], v[32:35], off
	s_nop 0
	s_and_b64 vcc, exec, s[8:9]
	s_waitcnt vmcnt(7)
	v_fmamk_f32 v32, v185, 0x3a800000, v222
	v_rsq_f32_e32 v32, v32
	s_cbranch_vccnz .LBB0_561
	global_load_dword v33, v[146:147], off offset:640
	v_mul_f32_e32 v34, v32, v32
	s_waitcnt vmcnt(0)
	v_mul_f32_e32 v33, v34, v33
	v_fmamk_f32 v33, v33, 0x3a800000, v222
	v_rsq_f32_e32 v33, v33
	s_nop 0
	v_mul_f32_e32 v32, v32, v33
; __device__ __forceinline__ unsigned cvt_pk_bf16(float lo, float hi) { unsigned r; asm volatile("v_cvt_pk_bf16_f32 %0, %1, %2" : "=v"(r) : "v"(lo), "v"(hi)); return r; }
; #define SWG_(gv, uv) ((gv) * (uv) * __builtin_amdgcn_rcpf(1.0f + __builtin_amdgcn_exp2f(-(gv))))
;     template <class T> __device__ __forceinline__ T* p(int i) const { const unsigned long long lo = u(i), hi = u(i + 1); return (T*)(__attribute__((address_space(1))) T*)((hi << 32) | lo); }
; __device__ __forceinline__ float row_scale(const float* ssqA, const float* ssqB, int row) {
;     float r = __builtin_amdgcn_rsqf(ssqA[row] * (1.0f / 1024.0f) + 1e-6f);
;     if (ssqB) r *= __builtin_amdgcn_rsqf(r * r * ssqB[row] * (1.0f / 1024.0f) + 1e-6f);
;     static __device__ __forceinline__ void run(const f32x4 (&acc)[2][2][4][2], const Unit& u, int wr, int wc, int fr, int fq, bf16_t* H, int ldh, const float* ssqA, const float* ssqB, const float* bvec) {
;     ...
;                 const int row = row0 + ai * HALF + m * 16; const float r = row_scale(ssqA, ssqB, row); const float rg = r * 1.4426950408889634f, ru = r * 0.6931471805599453f;
;                 bf16_t* p = H + ((unsigned)row * (unsigned)ldh + (unsigned)col0);
;                 const f32x4 g0 = acc[ai][0][m][0] * rg + bg0, g1 = acc[ai][0][m][1] * rg + bg1, u0 = acc[ai][1][m][0] * ru + bu0, u1 = acc[ai][1][m][1] * ru + bu1;
;                 u32x4 w;
;                 w.x = cvt_pk_bf16(SWG_(g0[0], u0[0]), SWG_(g0[1], u0[1]));
;                 w.y = cvt_pk_bf16(SWG_(g0[2], u0[2]), SWG_(g0[3], u0[3]));
;                 w.z = cvt_pk_bf16(SWG_(g1[0], u1[0]), SWG_(g1[1], u1[1]));
;                 w.w = cvt_pk_bf16(SWG_(g1[2], u1[2]), SWG_(g1[3], u1[3]));
;                 __builtin_nontemporal_store(w, (u32x4*)p);
.LBB0_561:
	v_mul_f32_e32 v34, 0x3fb8aa3b, v32
	v_pk_fma_f32 v[28:29], v[28:29], v[34:35], v[140:141] op_sel_hi:[1,0,1]
	v_mul_f32_e32 v36, 0x3f317218, v32
	v_exp_f32_e64 v33, -v28
	v_pk_fma_f32 v[30:31], v[30:31], v[34:35], v[142:143] op_sel_hi:[1,0,1]
	v_pk_fma_f32 v[26:27], v[26:27], v[34:35], v[138:139] op_sel_hi:[1,0,1]
	v_pk_fma_f32 v[24:25], v[24:25], v[34:35], v[136:137] op_sel_hi:[1,0,1]
	v_pk_fma_f32 v[34:35], v[18:19], v[36:37], v[130:131] op_sel_hi:[1,0,1]
	v_pk_fma_f32 v[18:19], v[16:17], v[36:37], v[128:129] op_sel_hi:[1,0,1]
	v_exp_f32_e64 v16, -v29
	v_add_f32_e32 v17, 1.0, v33
	v_rcp_f32_e32 v17, v17
	v_pk_fma_f32 v[20:21], v[20:21], v[36:37], v[132:133] op_sel_hi:[1,0,1]
	v_add_f32_e32 v16, 1.0, v16
	v_rcp_f32_e32 v16, v16
	v_mul_f32_e32 v20, v28, v20
	v_mul_f32_e32 v17, v20, v17
	v_mul_f32_e32 v20, v29, v21
	v_exp_f32_e64 v21, -v30
	v_mul_f32_e32 v16, v20, v16
	v_cvt_pk_bf16_f32 v16, v17, v16
	v_exp_f32_e64 v17, -v31
	v_add_f32_e32 v20, 1.0, v21
	v_rcp_f32_e32 v20, v20
	v_pk_fma_f32 v[22:23], v[22:23], v[36:37], v[134:135] op_sel_hi:[1,0,1]
	v_add_f32_e32 v17, 1.0, v17
	v_rcp_f32_e32 v17, v17
	v_mul_f32_e32 v21, v30, v22
	v_mul_f32_e32 v20, v21, v20
	v_mul_f32_e32 v21, v31, v23
	v_exp_f32_e64 v22, -v24
	v_mul_f32_e32 v17, v21, v17
	v_cvt_pk_bf16_f32 v17, v20, v17
	v_exp_f32_e64 v20, -v25
	v_add_f32_e32 v21, 1.0, v22
	v_rcp_f32_e32 v21, v21
	v_mul_f32_e32 v18, v24, v18
	v_add_f32_e32 v20, 1.0, v20
	v_rcp_f32_e32 v20, v20
	v_mul_f32_e32 v18, v18, v21
	v_mul_f32_e32 v19, v25, v19
	v_exp_f32_e64 v21, -v26
	v_mul_f32_e32 v19, v19, v20
	v_exp_f32_e64 v20, -v27
	v_cvt_pk_bf16_f32 v18, v18, v19
	v_add_f32_e32 v19, 1.0, v21
	v_rcp_f32_e32 v19, v19
	v_add_f32_e32 v20, 1.0, v20
	v_rcp_f32_e32 v20, v20
	v_add_u32_e32 v32, s10, v48
	v_add_u32_e32 v176, v32, v149
	v_mul_f32_e32 v21, v26, v34
	v_lshl_add_u64 v[38:39], v[176:177], 1, s[2:3]
	v_mul_f32_e32 v19, v21, v19
	v_mul_f32_e32 v21, v27, v35
	v_mul_f32_e32 v20, v21, v20
	v_cvt_pk_bf16_f32 v19, v19, v20
	global_store_dwordx4 v[38:39], v[16:19], off
	s_nop 0
	s_and_b64 vcc, exec, s[8:9]
	s_waitcnt vmcnt(7)
	v_fmamk_f32 v16, v186, 0x3a800000, v222
	v_rsq_f32_e32 v16, v16
	s_cbranch_vccnz .LBB0_563
	global_load_dword v17, v[146:147], off offset:704
	v_mul_f32_e32 v18, v16, v16
	s_waitcnt vmcnt(0)
	v_mul_f32_e32 v17, v18, v17
	v_fmamk_f32 v17, v17, 0x3a800000, v222
	v_rsq_f32_e32 v17, v17
	s_nop 0
	v_mul_f32_e32 v16, v16, v17
.LBB0_563:
	v_mul_f32_e32 v18, 0x3fb8aa3b, v16
	v_mul_f32_e32 v16, 0x3f317218, v16
	v_pk_fma_f32 v[12:13], v[12:13], v[18:19], v[140:141] op_sel_hi:[1,0,1]
	v_pk_fma_f32 v[6:7], v[6:7], v[16:17], v[134:135] op_sel_hi:[1,0,1]
	v_pk_fma_f32 v[4:5], v[4:5], v[16:17], v[132:133] op_sel_hi:[1,0,1]
	v_exp_f32_e64 v17, -v12
	v_pk_fma_f32 v[14:15], v[14:15], v[18:19], v[142:143] op_sel_hi:[1,0,1]
	v_pk_fma_f32 v[10:11], v[10:11], v[18:19], v[138:139] op_sel_hi:[1,0,1]
	v_pk_fma_f32 v[8:9], v[8:9], v[18:19], v[136:137] op_sel_hi:[1,0,1]
	v_pk_fma_f32 v[18:19], v[2:3], v[16:17], v[130:131] op_sel_hi:[1,0,1]
	v_pk_fma_f32 v[2:3], v[0:1], v[16:17], v[128:129] op_sel_hi:[1,0,1]
	v_exp_f32_e64 v0, -v13
	v_add_f32_e32 v1, 1.0, v17
	v_rcp_f32_e32 v1, v1
	v_mul_f32_e32 v4, v12, v4
	v_add_f32_e32 v0, 1.0, v0
	v_rcp_f32_e32 v0, v0
	v_mul_f32_e32 v1, v4, v1
	v_mul_f32_e32 v4, v13, v5
	v_exp_f32_e64 v5, -v14
	v_mul_f32_e32 v0, v4, v0
	v_cvt_pk_bf16_f32 v0, v1, v0
	v_exp_f32_e64 v1, -v15
	v_add_f32_e32 v4, 1.0, v5
	v_rcp_f32_e32 v4, v4
	v_mul_f32_e32 v5, v14, v6
	v_add_f32_e32 v1, 1.0, v1
	v_rcp_f32_e32 v1, v1
	v_mul_f32_e32 v4, v5, v4
	v_mul_f32_e32 v5, v15, v7
	v_exp_f32_e64 v6, -v8
	v_mul_f32_e32 v1, v5, v1
	v_cvt_pk_bf16_f32 v1, v4, v1
	v_exp_f32_e64 v4, -v9
	v_add_f32_e32 v5, 1.0, v6
	v_rcp_f32_e32 v5, v5
	v_mul_f32_e32 v2, v8, v2
	v_add_f32_e32 v4, 1.0, v4
	v_rcp_f32_e32 v4, v4
	v_mul_f32_e32 v2, v2, v5
	v_mul_f32_e32 v3, v9, v3
	v_exp_f32_e64 v5, -v10
	v_mul_f32_e32 v3, v3, v4
	v_exp_f32_e64 v4, -v11
	v_cvt_pk_bf16_f32 v2, v2, v3
	v_add_f32_e32 v3, 1.0, v5
	v_rcp_f32_e32 v3, v3
	v_add_f32_e32 v4, 1.0, v4
	v_rcp_f32_e32 v4, v4
	v_add3_u32 v176, v32, s10, v149
	v_mul_f32_e32 v5, v10, v18
	v_lshl_add_u64 v[20:21], v[176:177], 1, s[2:3]
	v_mul_f32_e32 v3, v5, v3
	v_mul_f32_e32 v5, v11, v19
	v_mul_f32_e32 v4, v5, v4
	v_cvt_pk_bf16_f32 v3, v3, v4
	global_store_dwordx4 v[20:21], v[0:3], off
